# scan wave: removed 62 s_nop 0 hazard pads between inline-asm v_fma (not real hazards)
# speedup vs baseline: 1.0037x; 1.0037x over previous
.LBB0_332:
	s_waitcnt lgkmcnt(0)
	s_barrier
	s_andn2_b64 vcc, exec, s[4:5]
	s_cbranch_vccnz .LBB0_329
	s_mul_i32 s4, s12, 0x2800
	v_xor_b32_e32 v88, 0x80000000, v87
	s_waitcnt lgkmcnt(14)
	v_fma_f32 v89, v88, v85, v12
	s_waitcnt lgkmcnt(11)
	v_fma_f32 v90, v87, v86, v44
	s_xor_b32 s12, s12, 1
	v_fma_f32 v86, v116, v86, v89
	v_fma_f32 v85, v116, v85, v90
	v_add_u32_e32 v90, s4, v110
	v_cvt_pk_bf16_f32 v89, v86, v85
	ds_write_b32 v90, v89 offset:18432
	v_fma_f32 v89, v88, v85, v13
	v_fma_f32 v91, v87, v86, v45
	v_fma_f32 v86, v116, v86, v89
	v_fma_f32 v85, v116, v85, v91
	v_cvt_pk_bf16_f32 v89, v86, v85
	ds_write_b32 v90, v89 offset:18752
	v_fma_f32 v89, v88, v85, v14
	v_fma_f32 v91, v87, v86, v46
	v_fma_f32 v86, v116, v86, v89
	v_fma_f32 v85, v116, v85, v91
	v_cvt_pk_bf16_f32 v89, v86, v85
	ds_write_b32 v90, v89 offset:19072
	v_fma_f32 v89, v88, v85, v15
	v_fma_f32 v91, v87, v86, v47
	v_fma_f32 v86, v116, v86, v89
	v_fma_f32 v85, v116, v85, v91
	v_cvt_pk_bf16_f32 v89, v86, v85
	ds_write_b32 v90, v89 offset:19392
	v_fma_f32 v89, v88, v85, v8
	s_waitcnt lgkmcnt(14)
	v_fma_f32 v91, v87, v86, v40
	v_fma_f32 v86, v116, v86, v89
	v_fma_f32 v85, v116, v85, v91
	v_cvt_pk_bf16_f32 v89, v86, v85
	ds_write_b32 v90, v89 offset:19712
	v_fma_f32 v89, v88, v85, v9
	v_fma_f32 v91, v87, v86, v41
	v_fma_f32 v86, v116, v86, v89
	v_fma_f32 v85, v116, v85, v91
	v_cvt_pk_bf16_f32 v89, v86, v85
	ds_write_b32 v90, v89 offset:20032
	v_fma_f32 v89, v88, v85, v10
	v_fma_f32 v91, v87, v86, v42
	v_fma_f32 v86, v116, v86, v89
	v_fma_f32 v85, v116, v85, v91
	v_cvt_pk_bf16_f32 v89, v86, v85
	ds_write_b32 v90, v89 offset:20352
	v_fma_f32 v89, v88, v85, v11
	v_fma_f32 v91, v87, v86, v43
	v_fma_f32 v86, v116, v86, v89
	v_fma_f32 v85, v116, v85, v91
	v_cvt_pk_bf16_f32 v89, v86, v85
	ds_write_b32 v90, v89 offset:20672
	v_fma_f32 v89, v88, v85, v4
	s_waitcnt lgkmcnt(14)
	v_fma_f32 v91, v87, v86, v36
	v_fma_f32 v86, v116, v86, v89
	v_fma_f32 v85, v116, v85, v91
	v_cvt_pk_bf16_f32 v89, v86, v85
	ds_write_b32 v90, v89 offset:20992
	v_fma_f32 v89, v88, v85, v5
	v_fma_f32 v91, v87, v86, v37
	v_fma_f32 v86, v116, v86, v89
	v_fma_f32 v85, v116, v85, v91
	v_cvt_pk_bf16_f32 v89, v86, v85
	ds_write_b32 v90, v89 offset:21312
	v_fma_f32 v89, v88, v85, v6
	v_fma_f32 v91, v87, v86, v38
	v_fma_f32 v86, v116, v86, v89
	v_fma_f32 v85, v116, v85, v91
	v_cvt_pk_bf16_f32 v89, v86, v85
	ds_write_b32 v90, v89 offset:21632
	v_fma_f32 v89, v88, v85, v7
	v_fma_f32 v91, v87, v86, v39
	v_fma_f32 v86, v116, v86, v89
	v_fma_f32 v85, v116, v85, v91
	v_cvt_pk_bf16_f32 v89, v86, v85
	ds_write_b32 v90, v89 offset:21952
	v_fma_f32 v89, v88, v85, v0
	v_fma_f32 v91, v87, v86, v32
	v_fma_f32 v86, v116, v86, v89
	v_fma_f32 v85, v116, v85, v91
	v_cvt_pk_bf16_f32 v89, v86, v85
	ds_write_b32 v90, v89 offset:22272
	v_fma_f32 v89, v88, v85, v1
	v_fma_f32 v91, v87, v86, v33
	v_fma_f32 v86, v116, v86, v89
	v_fma_f32 v85, v116, v85, v91
	v_cvt_pk_bf16_f32 v89, v86, v85
	ds_write_b32 v90, v89 offset:22592
	v_fma_f32 v89, v88, v85, v2
	v_fma_f32 v91, v87, v86, v34
	v_fma_f32 v86, v116, v86, v89
	v_fma_f32 v85, v116, v85, v91
	v_cvt_pk_bf16_f32 v89, v86, v85
	ds_write_b32 v90, v89 offset:22912
	v_fma_f32 v89, v88, v85, v3
	v_fma_f32 v91, v87, v86, v35
	v_fma_f32 v86, v116, v86, v89
	v_fma_f32 v85, v116, v85, v91
	v_cvt_pk_bf16_f32 v89, v86, v85
	ds_write_b32 v90, v89 offset:23232
	v_fma_f32 v89, v88, v85, v16
	s_waitcnt lgkmcnt(14)
	v_fma_f32 v91, v87, v86, v52
	v_fma_f32 v86, v116, v86, v89
	v_fma_f32 v85, v116, v85, v91
	v_cvt_pk_bf16_f32 v89, v86, v85
	ds_write_b32 v90, v89 offset:23552
	v_fma_f32 v89, v88, v85, v17
	v_fma_f32 v91, v87, v86, v53
	v_fma_f32 v86, v116, v86, v89
	v_fma_f32 v85, v116, v85, v91
	v_cvt_pk_bf16_f32 v89, v86, v85
	ds_write_b32 v90, v89 offset:23872
	v_fma_f32 v89, v88, v85, v18
	v_fma_f32 v91, v87, v86, v54
	v_fma_f32 v86, v116, v86, v89
	v_fma_f32 v85, v116, v85, v91
	v_cvt_pk_bf16_f32 v89, v86, v85
	ds_write_b32 v90, v89 offset:24192
	v_fma_f32 v89, v88, v85, v19
	v_fma_f32 v91, v87, v86, v55
	v_fma_f32 v86, v116, v86, v89
	v_fma_f32 v85, v116, v85, v91
	v_cvt_pk_bf16_f32 v89, v86, v85
	ds_write_b32 v90, v89 offset:24512
	v_fma_f32 v89, v88, v85, v20
	v_fma_f32 v91, v87, v86, v48
	v_fma_f32 v86, v116, v86, v89
	v_fma_f32 v85, v116, v85, v91
	v_cvt_pk_bf16_f32 v89, v86, v85
	ds_write_b32 v90, v89 offset:24832
	v_fma_f32 v89, v88, v85, v21
	v_fma_f32 v91, v87, v86, v49
	v_fma_f32 v86, v116, v86, v89
	v_fma_f32 v85, v116, v85, v91
	v_cvt_pk_bf16_f32 v89, v86, v85
	ds_write_b32 v90, v89 offset:25152
	v_fma_f32 v89, v88, v85, v22
	v_fma_f32 v91, v87, v86, v50
	v_fma_f32 v86, v116, v86, v89
	v_fma_f32 v85, v116, v85, v91
	v_cvt_pk_bf16_f32 v89, v86, v85
	ds_write_b32 v90, v89 offset:25472
	v_fma_f32 v89, v88, v85, v23
	v_fma_f32 v91, v87, v86, v51
	v_fma_f32 v86, v116, v86, v89
	v_fma_f32 v85, v116, v85, v91
	v_cvt_pk_bf16_f32 v89, v86, v85
	ds_write_b32 v90, v89 offset:25792
	v_fma_f32 v89, v88, v85, v24
	v_fma_f32 v91, v87, v86, v60
	v_fma_f32 v86, v116, v86, v89
	v_fma_f32 v85, v116, v85, v91
	v_cvt_pk_bf16_f32 v89, v86, v85
	ds_write_b32 v90, v89 offset:26112
	v_fma_f32 v89, v88, v85, v25
	v_fma_f32 v91, v87, v86, v61
	v_fma_f32 v86, v116, v86, v89
	v_fma_f32 v85, v116, v85, v91
	v_cvt_pk_bf16_f32 v89, v86, v85
	ds_write_b32 v90, v89 offset:26432
	v_fma_f32 v89, v88, v85, v26
	v_fma_f32 v91, v87, v86, v62
	v_fma_f32 v86, v116, v86, v89
	v_fma_f32 v85, v116, v85, v91
	v_cvt_pk_bf16_f32 v89, v86, v85
	ds_write_b32 v90, v89 offset:26752
	v_fma_f32 v89, v88, v85, v27
	v_fma_f32 v91, v87, v86, v63
	v_fma_f32 v86, v116, v86, v89
	v_fma_f32 v85, v116, v85, v91
	v_cvt_pk_bf16_f32 v89, v86, v85
	ds_write_b32 v90, v89 offset:27072
	v_fma_f32 v89, v88, v85, v28
	v_fma_f32 v91, v87, v86, v56
	v_fma_f32 v86, v116, v86, v89
	v_fma_f32 v85, v116, v85, v91
	v_cvt_pk_bf16_f32 v89, v86, v85
	ds_write_b32 v90, v89 offset:27392
	v_fma_f32 v89, v88, v85, v29
	v_fma_f32 v91, v87, v86, v57
	v_fma_f32 v86, v116, v86, v89
	v_fma_f32 v85, v116, v85, v91
	v_cvt_pk_bf16_f32 v89, v86, v85
	ds_write_b32 v90, v89 offset:27712
	v_fma_f32 v89, v88, v85, v30
	v_fma_f32 v91, v87, v86, v58
	v_fma_f32 v86, v116, v86, v89
	v_fma_f32 v85, v116, v85, v91
	v_cvt_pk_bf16_f32 v89, v86, v85
	v_fma_f32 v88, v88, v85, v31
	ds_write_b32 v90, v89 offset:28032
	v_fma_f32 v89, v87, v86, v59
	v_fma_f32 v86, v116, v86, v88
	v_fma_f32 v85, v116, v85, v89
	v_cvt_pk_bf16_f32 v88, v86, v85
	ds_write_b32 v90, v88 offset:28352
	s_branch .LBB0_329
